# convert_layer (in-loop): fp8 gate-weight conversion loop issues its 8 strided loads together (was 8 serialized round trips per iteration)
# speedup vs baseline: 1.0164x; 1.0025x over previous
; __device__ __forceinline__ unsigned pack4_fp8(float a, float b, float c, float d) { unsigned w = 0u; w = __builtin_amdgcn_cvt_pk_fp8_f32(a, b, w, false); w = __builtin_amdgcn_cvt_pk_fp8_f32(c, d, w, true); return w; }
; __device__ __forceinline__ void convert_layer(unsigned char* smem, const Params& P, int layer, int skip) {
;     ...
;     { const float* src = P.w_in + (size_t)layer * DM * INW + ZW; const float* gain = P.norm_mix + layer * DM; unsigned char* dst = (unsigned char*)(wb + W_G);
;       for (size_t idx = (size_t)vb * 512 + tidx; idx < (size_t)3072 * 128; idx += (size_t)vG * 512) { const int n = (int)(idx % 3072), k8 = (int)(idx / 3072); float v[8];
; #pragma unroll
;           for (int j = 0; j < 8; ++j) v[j] = src[(size_t)(k8 * 8 + j) * INW + n] * gain[k8 * 8 + j] * GATE_WSCALE;
;           u32x2 w8; w8.x = pack4_fp8(v[0], v[1], v[2], v[3]); w8.y = pack4_fp8(v[4], v[5], v[6], v[7]); *(u32x2*)(dst + (size_t)n * 1024 + k8 * 8) = w8; } }
.LBB0_649:
	s_mov_b32 s4, 0xaaaaaaab
	v_mul_hi_u32 v0, v10, s4
	v_lshrrev_b32_e32 v16, 11, v0
	v_mul_u32_u24_e32 v0, 0xc00, v16
	v_sub_u32_e32 v0, v10, v0
	v_lshlrev_b32_e32 v12, 3, v16
	v_lshl_add_u64 v[22:23], v[0:1], 2, s[40:41]
	v_lshlrev_b32_e32 v18, 5, v16
	global_load_dwordx4 v[30:33], v18, s[6:7]
	global_load_dwordx4 v[34:37], v18, s[6:7] offset:16
	v_mov_b32_e32 v24, v12
	v_mad_u64_u32 v[24:25], s[4:5], v24, s29, v[22:23]
	global_load_dword v40, v[24:25], off
	v_or_b32_e32 v24, 1, v12
	v_mad_u64_u32 v[24:25], s[4:5], v24, s29, v[22:23]
	global_load_dword v41, v[24:25], off
	v_or_b32_e32 v24, 2, v12
	v_mad_u64_u32 v[24:25], s[4:5], v24, s29, v[22:23]
	global_load_dword v42, v[24:25], off
	v_or_b32_e32 v24, 3, v12
	v_mad_u64_u32 v[24:25], s[4:5], v24, s29, v[22:23]
	global_load_dword v43, v[24:25], off
	v_or_b32_e32 v24, 4, v12
	v_mad_u64_u32 v[24:25], s[4:5], v24, s29, v[22:23]
	global_load_dword v44, v[24:25], off
	v_or_b32_e32 v24, 5, v12
	v_mad_u64_u32 v[24:25], s[4:5], v24, s29, v[22:23]
	global_load_dword v45, v[24:25], off
	v_or_b32_e32 v24, 6, v12
	v_mad_u64_u32 v[24:25], s[4:5], v24, s29, v[22:23]
	global_load_dword v46, v[24:25], off
	v_or_b32_e32 v24, 7, v12
	v_mad_u64_u32 v[24:25], s[4:5], v24, s29, v[22:23]
	global_load_dword v47, v[24:25], off
	v_lshl_add_u64 v[10:11], v[10:11], 0, s[44:45]
	v_mov_b32_e32 v13, v1
	s_waitcnt vmcnt(0)
	v_mul_f32_e32 v40, v40, v30
	v_mul_f32_e32 v40, 0x42800000, v40
	v_mul_f32_e32 v41, v41, v31
	v_mul_f32_e32 v41, 0x42800000, v41
	v_mul_f32_e32 v42, v42, v32
	v_mul_f32_e32 v42, 0x42800000, v42
	v_mul_f32_e32 v43, v43, v33
	v_mul_f32_e32 v43, 0x42800000, v43
	v_mul_f32_e32 v44, v44, v34
	v_mul_f32_e32 v44, 0x42800000, v44
	v_mul_f32_e32 v45, v45, v35
	v_mul_f32_e32 v45, 0x42800000, v45
	v_mul_f32_e32 v46, v46, v36
	v_mul_f32_e32 v46, 0x42800000, v46
	v_mul_f32_e32 v47, v47, v37
	v_mul_f32_e32 v47, 0x42800000, v47
	v_mov_b32_e32 v14, v1
	v_mov_b32_e32 v15, v1
	v_cvt_pk_fp8_f32 v14, v40, v41
	v_cvt_pk_fp8_f32 v15, v44, v45
	v_lshlrev_b64 v[16:17], 10, v[0:1]
	v_cvt_pk_fp8_f32 v14, v42, v43 op_sel:[0,0,1]
	v_cvt_pk_fp8_f32 v15, v46, v47 op_sel:[0,0,1]
	v_lshl_add_u64 v[16:17], s[42:43], 0, v[16:17]
	v_lshl_add_u64 v[12:13], v[16:17], 0, v[12:13]
	s_mov_b64 s[4:5], 0x5ffff
	v_cmp_lt_u64_e32 vcc, s[4:5], v[10:11]
	s_or_b64 s[50:51], vcc, s[50:51]
	global_store_dwordx2 v[12:13], v[14:15], off
	s_andn2_b64 exec, exec, s[50:51]
	s_cbranch_execnz .LBB0_649
